# v93 variant: two-pass-A waves take 2 rows (was 3), 1152 waves x 11 + 64 x 10
# speedup vs baseline: 1.0084x; 1.0037x over previous
.LBB0_447:
	s_and_b64 vcc, exec, s[0:1]
	s_cbranch_vccz .LBB0_557
	s_movk_i32 s0, 0xff
	v_cmp_lt_i32_e32 vcc, s0, v81
	s_and_saveexec_b64 s[0:1], vcc
	s_xor_b64 s[42:43], exec, s[0:1]
	s_cbranch_execz .LBB0_531
	s_movk_i32 s0, 0x33f
	v_cmp_lt_u32_e32 vcc, s0, v81
	s_and_saveexec_b64 s[0:1], vcc
	s_xor_b64 s[16:17], exec, s[0:1]
	s_cbranch_execz .LBB0_501
	s_movk_i32 s0, 0x7bf
	v_cmp_lt_u32_e32 vcc, s0, v81
	v_readlane_b32 s4, v254, 28
	v_readlane_b32 s0, v255, 7
	v_readlane_b32 s5, v254, 29
	s_add_u32 s2, s4, 0x16f00000
	v_readlane_b32 s1, v255, 8
	s_addc_u32 s3, s5, 0
	s_lshl_b64 s[0:1], s[0:1], 2
	s_add_u32 s0, s4, s0
	s_addc_u32 s1, s5, s1
	s_add_u32 s18, s0, 0x2000
	s_addc_u32 s19, s1, 0
	s_and_saveexec_b64 s[0:1], vcc
	s_xor_b64 s[28:29], exec, s[0:1]
	s_cbranch_execz .LBB0_475
	v_mov_b32_e32 v0, 0xfffff800
	v_mov_b32_e32 v1, -1
	v_mad_u64_u32 v[8:9], s[0:1], v81, 10, v[0:1]
	v_mov_b32_e32 v9, v236
	v_readlane_b32 s4, v255, 11
	v_and_b32_e32 v17, 15, v9
	v_bfe_u32 v19, v9, 4, 2
	v_lshlrev_b32_e32 v21, 2, v17
	v_lshlrev_b32_e32 v12, 6, v19
	v_or_b32_e32 v23, 8, v19
	v_readlane_b32 s5, v255, 12
	v_or_b32_e32 v20, 0x100, v21
	v_min_u32_e32 v0, 9, v23
	v_mov_b64_e32 v[10:11], s[4:5]
	s_movk_i32 s0, 0x1200
	v_or_b32_e32 v22, v12, v21
	v_or_b32_e32 v16, v12, v20
	v_lshlrev_b32_e32 v25, 6, v0
	v_mad_i64_i32 v[10:11], s[0:1], v8, s0, v[10:11]
	v_lshlrev_b32_e32 v160, 1, v22
	v_lshl_add_u64 v[12:13], v[10:11], 0, v[160:161]
	v_lshlrev_b32_e32 v160, 1, v16
	v_or_b32_e32 v24, v25, v21
	v_lshlrev_b32_e32 v4, 4, v17
	v_lshl_add_u64 v[14:15], v[10:11], 0, v[160:161]
	v_lshlrev_b32_e32 v160, 1, v24
	global_load_dwordx4 v[0:3], v4, s[18:19]
	s_nop 0
	global_load_dwordx4 v[4:7], v4, s[18:19] offset:1024
	v_lshl_add_u64 v[10:11], v[10:11], 0, v[160:161]
	global_load_dwordx2 v[46:47], v[12:13], off offset:512
	global_load_dwordx2 v[44:45], v[14:15], off offset:512
	global_load_dwordx2 v[38:39], v[10:11], off offset:512
	v_and_b32_e32 v10, 63, v9
	v_and_b32_e32 v9, 4, v9
	v_cmp_eq_u32_e64 s[36:37], 0, v9
	v_and_b32_e32 v9, 12, v21
	v_cvt_f32_ubyte0_e32 v14, v9
	v_mul_f32_e32 v14, 0xbf549a78, v14
	v_exp_f32_e32 v59, v14
	v_or_b32_e32 v14, 1, v9
	v_cvt_f32_ubyte0_e32 v14, v14
	v_mul_f32_e32 v14, 0xbf549a78, v14
	v_exp_f32_e32 v60, v14
	v_or_b32_e32 v14, 2, v9
	v_or_b32_e32 v9, 3, v9
	v_cvt_f32_ubyte0_e32 v14, v14
	v_cvt_f32_ubyte0_e32 v9, v9
	v_mul_f32_e32 v14, 0xbf549a78, v14
	v_mul_f32_e32 v9, 0xbf549a78, v9
	v_exp_f32_e32 v61, v14
	v_exp_f32_e32 v62, v9
	v_readlane_b32 s0, v254, 28
	v_add_u32_e32 v18, 0x100, v16
	v_or_b32_e32 v20, v25, v20
	v_mov_b32_e32 v64, 0
	v_lshlrev_b32_e32 v160, 3, v10
	v_readlane_b32 s1, v254, 29
	v_cmp_gt_u32_e32 vcc, 10, v23
	v_lshlrev_b32_e64 v58, v19, 1
	v_lshl_add_u64 v[10:11], s[4:5], 0, v[160:161]
	v_cmp_gt_u32_e64 s[38:39], 8, v17
	v_lshl_add_u64 v[12:13], s[2:3], 0, v[160:161]
	v_lshl_add_u64 v[14:15], s[0:1], 0, v[160:161]
	s_mov_b32 s14, 0
	v_lshlrev_b32_e32 v16, 1, v16
	v_lshlrev_b32_e32 v18, 1, v18
	v_lshlrev_b32_e32 v20, 1, v20
	v_lshlrev_b32_e32 v22, 1, v22
	v_lshlrev_b32_e32 v24, 1, v24
	v_mov_b32_e32 v63, v8
	v_mov_b32_e32 v23, 0
	v_mov_b32_e32 v40, 0
	v_mov_b32_e32 v41, v64
	v_mov_b32_e32 v42, 0
	v_mov_b32_e32 v43, v64
	s_branch .LBB0_453

.LBB0_475:
	s_andn2_saveexec_b64 s[28:29], s[28:29]
	s_cbranch_execz .LBB0_500
	v_mov_b32_e32 v0, 0xfffff040
	v_mov_b32_e32 v1, -1
	v_mad_u64_u32 v[8:9], s[0:1], v81, 11, v[0:1]
	v_mov_b32_e32 v9, v236
	v_readlane_b32 s4, v255, 11
	v_and_b32_e32 v17, 15, v9
	v_bfe_u32 v19, v9, 4, 2
	v_lshlrev_b32_e32 v21, 2, v17
	v_lshlrev_b32_e32 v12, 6, v19
	v_or_b32_e32 v23, 8, v19
	v_readlane_b32 s5, v255, 12
	v_or_b32_e32 v20, 0x100, v21
	v_min_u32_e32 v0, 9, v23
	v_mov_b64_e32 v[10:11], s[4:5]
	s_movk_i32 s0, 0x1200
	v_or_b32_e32 v22, v12, v21
	v_or_b32_e32 v16, v12, v20
	v_lshlrev_b32_e32 v25, 6, v0
	v_mad_u64_u32 v[10:11], s[0:1], v8, s0, v[10:11]
	v_lshlrev_b32_e32 v160, 1, v22
	v_lshl_add_u64 v[12:13], v[10:11], 0, v[160:161]
	v_lshlrev_b32_e32 v160, 1, v16
	v_or_b32_e32 v24, v25, v21
	v_lshlrev_b32_e32 v4, 4, v17
	v_lshl_add_u64 v[14:15], v[10:11], 0, v[160:161]
	v_lshlrev_b32_e32 v160, 1, v24
	global_load_dwordx4 v[0:3], v4, s[18:19]
	s_nop 0
	global_load_dwordx4 v[4:7], v4, s[18:19] offset:1024
	v_lshl_add_u64 v[10:11], v[10:11], 0, v[160:161]
	global_load_dwordx2 v[46:47], v[12:13], off offset:512
	global_load_dwordx2 v[44:45], v[14:15], off offset:512
	global_load_dwordx2 v[38:39], v[10:11], off offset:512
	v_and_b32_e32 v10, 63, v9
	v_and_b32_e32 v9, 4, v9
	v_cmp_eq_u32_e64 s[36:37], 0, v9
	v_and_b32_e32 v9, 12, v21
	v_cvt_f32_ubyte0_e32 v14, v9
	v_mul_f32_e32 v14, 0xbf549a78, v14
	v_exp_f32_e32 v59, v14
	v_or_b32_e32 v14, 1, v9
	v_cvt_f32_ubyte0_e32 v14, v14
	v_mul_f32_e32 v14, 0xbf549a78, v14
	v_exp_f32_e32 v60, v14
	v_or_b32_e32 v14, 2, v9
	v_or_b32_e32 v9, 3, v9
	v_cvt_f32_ubyte0_e32 v14, v14
	v_cvt_f32_ubyte0_e32 v9, v9
	v_mul_f32_e32 v14, 0xbf549a78, v14
	v_mul_f32_e32 v9, 0xbf549a78, v9
	v_exp_f32_e32 v61, v14
	v_exp_f32_e32 v62, v9
	v_readlane_b32 s0, v254, 28
	v_add_u32_e32 v18, 0x100, v16
	v_or_b32_e32 v20, v25, v20
	v_mov_b32_e32 v64, 0
	v_lshlrev_b32_e32 v160, 3, v10
	v_readlane_b32 s1, v254, 29
	v_cmp_gt_u32_e32 vcc, 10, v23
	v_lshlrev_b32_e64 v58, v19, 1
	v_lshl_add_u64 v[10:11], s[4:5], 0, v[160:161]
	v_cmp_gt_u32_e64 s[38:39], 8, v17
	v_lshl_add_u64 v[12:13], s[2:3], 0, v[160:161]
	v_lshl_add_u64 v[14:15], s[0:1], 0, v[160:161]
	s_mov_b32 s10, 0
	v_lshlrev_b32_e32 v16, 1, v16
	v_lshlrev_b32_e32 v18, 1, v18
	v_lshlrev_b32_e32 v20, 1, v20
	v_lshlrev_b32_e32 v22, 1, v22
	v_lshlrev_b32_e32 v24, 1, v24
	v_mov_b32_e32 v63, v8
	v_mov_b32_e32 v23, 0
	v_mov_b32_e32 v40, 0
	v_mov_b32_e32 v41, v64
	v_mov_b32_e32 v42, 0
	v_mov_b32_e32 v43, v64
	s_branch .LBB0_478

.LBB0_501:
	s_andn2_saveexec_b64 s[2:3], s[16:17]
	s_cbranch_execz .LBB0_530
	v_add_u32_e32 v4, 0xffffff00, v81
	s_mov_b32 s0, 0xe38f
	v_mul_u32_u24_sdwa v1, v4, s0 dst_sel:DWORD dst_unused:UNUSED_PAD src0_sel:WORD_0 src1_sel:DWORD
	v_lshrrev_b32_e32 v2, 21, v1
	v_mul_lo_u16_e32 v3, 36, v2
	v_sub_u16_e32 v3, v4, v3
	v_mov_b32_e32 v0, v236
	v_lshrrev_b32_e32 v5, 22, v1
	v_cmp_lt_u16_e32 vcc, 31, v3
	v_lshlrev_b16_e32 v3, 6, v3
	s_and_saveexec_b64 s[0:1], vcc
	s_xor_b64 s[0:1], exec, s[0:1]
	v_lshlrev_b32_e32 v1, 8, v5
	s_movk_i32 s4, 0x3800
	v_add3_u32 v1, v3, v1, s4
	s_andn2_saveexec_b64 s[0:1], s[0:1]
	v_lshl_or_b32 v1, v5, 11, v3
	s_or_b64 exec, exec, s[0:1]
	v_readlane_b32 s8, v254, 28
	v_readlane_b32 s9, v254, 29
	s_movk_i32 s6, 0x1200
	v_lshlrev_b32_e32 v8, 7, v2
	v_mov_b64_e32 v[6:7], s[8:9]
	v_and_b32_e32 v5, 63, v0
	v_mad_u64_u32 v[0:1], s[0:1], v1, s6, v[6:7]
	v_and_b32_e32 v160, 0x80, v8
	v_lshl_add_u64 v[0:1], v[0:1], 0, v[160:161]
	v_lshlrev_b32_e32 v160, 1, v5
	v_lshl_add_u64 v[0:1], v[0:1], 0, v[160:161]
	s_mov_b32 s0, 0xb200000
	v_add_co_u32_e32 v8, vcc, s0, v0
	s_mov_b32 s0, 0xb201000
	s_nop 0
	v_addc_co_u32_e32 v9, vcc, 0, v1, vcc
	v_add_co_u32_e32 v10, vcc, s0, v0
	s_mov_b32 s0, 0xb202000
	s_nop 0
	v_addc_co_u32_e32 v11, vcc, 0, v1, vcc
	v_add_co_u32_e32 v12, vcc, s0, v0
	s_mov_b32 s0, 0xb203000
	s_nop 0
	v_addc_co_u32_e32 v13, vcc, 0, v1, vcc
	v_add_co_u32_e32 v14, vcc, s0, v0
	s_mov_b32 s0, 0xb204000
	s_nop 0
	v_addc_co_u32_e32 v15, vcc, 0, v1, vcc
	v_add_co_u32_e32 v16, vcc, s0, v0
	s_mov_b32 s0, 0xb206000
	s_nop 0
	v_addc_co_u32_e32 v17, vcc, 0, v1, vcc
	v_add_co_u32_e32 v18, vcc, s0, v0
	s_mov_b32 s0, 0xb207000
	s_nop 0
	v_addc_co_u32_e32 v19, vcc, 0, v1, vcc
	v_add_co_u32_e32 v20, vcc, s0, v0
	s_mov_b32 s0, 0xb208000
	s_nop 0
	v_addc_co_u32_e32 v21, vcc, 0, v1, vcc
	v_add_co_u32_e32 v22, vcc, s0, v0
	v_lshl_or_b32 v2, v2, 6, v5
	s_nop 0
	v_addc_co_u32_e32 v23, vcc, 0, v1, vcc
	global_load_ushort v8, v[8:9], off offset:1792
	s_nop 0
	global_load_ushort v9, v[10:11], off offset:2304
	global_load_ushort v24, v[12:13], off offset:2816
	global_load_ushort v25, v[14:15], off offset:3328
	global_load_ushort v26, v[16:17], off offset:3840
	global_load_ushort v27, v[18:19], off offset:256
	global_load_ushort v28, v[20:21], off offset:768
	global_load_ushort v29, v[22:23], off offset:1280
	v_mad_u64_u32 v[6:7], s[0:1], v2, s6, v[6:7]
	s_mov_b32 s0, 0xb209000
	s_nop 0
	v_add_co_u32_e32 v10, vcc, s0, v0
	s_mov_b32 s0, 0xb20a000
	s_nop 0
	v_addc_co_u32_e32 v11, vcc, 0, v1, vcc
	v_add_co_u32_e32 v12, vcc, s0, v0
	s_mov_b32 s0, 0xb20b000
	s_nop 0
	v_addc_co_u32_e32 v13, vcc, 0, v1, vcc
	v_add_co_u32_e32 v14, vcc, s0, v0
	s_mov_b32 s0, 0xb20c000
	s_nop 0
	v_addc_co_u32_e32 v15, vcc, 0, v1, vcc
	v_add_co_u32_e32 v16, vcc, s0, v0
	s_mov_b32 s0, 0xb20d000
	s_nop 0
	v_addc_co_u32_e32 v17, vcc, 0, v1, vcc
	v_add_co_u32_e32 v18, vcc, s0, v0
	s_mov_b32 s0, 0xb20f000
	s_nop 0
	v_addc_co_u32_e32 v19, vcc, 0, v1, vcc
	v_lshlrev_b32_e32 v160, 1, v3
	v_add_co_u32_e32 v20, vcc, s0, v0
	v_lshl_add_u64 v[2:3], v[6:7], 0, v[160:161]
	s_nop 0
	v_addc_co_u32_e32 v21, vcc, 0, v1, vcc
	s_mov_b32 s0, 0x19300000
	v_add_co_u32_e32 v22, vcc, s0, v2
	s_mov_b32 s0, 0xb210000
	s_nop 0
	v_addc_co_u32_e32 v23, vcc, 0, v3, vcc
	v_readlane_b32 s10, v255, 11
	v_readlane_b32 s11, v255, 12
	v_mov_b32_e32 v60, 0
	s_mov_b32 s14, 0
	v_mov_b32_e32 v38, 0
	v_mov_b32_e32 v39, v60
	v_mov_b32_e32 v36, 0
	v_mov_b32_e32 v37, v60
	s_waitcnt vmcnt(0)
	v_lshl_or_b32 v6, v9, 16, v8
	v_lshl_or_b32 v7, v25, 16, v24
	v_lshl_or_b32 v8, v27, 16, v26
	v_lshl_or_b32 v9, v29, 16, v28
	global_store_dwordx4 v[22:23], v[6:9], off
	s_nop 1
	v_add_co_u32_e32 v6, vcc, s0, v0
	s_mov_b32 s0, 0xb211000
	s_nop 0
	v_addc_co_u32_e32 v7, vcc, 0, v1, vcc
	v_add_co_u32_e32 v8, vcc, s0, v0
	s_mov_b32 s0, 0xb212000
	s_nop 0
	v_addc_co_u32_e32 v9, vcc, 0, v1, vcc
	global_load_ushort v5, v[10:11], off offset:1792
	global_load_ushort v26, v[12:13], off offset:2304
	global_load_ushort v27, v[14:15], off offset:2816
	global_load_ushort v28, v[16:17], off offset:3328
	global_load_ushort v29, v[18:19], off offset:3840
	global_load_ushort v30, v[20:21], off offset:256
	global_load_ushort v31, v[6:7], off offset:768
	s_nop 0
	global_load_ushort v9, v[8:9], off offset:1280
	v_add_co_u32_e32 v10, vcc, s0, v0
	s_mov_b32 s0, 0xb213000
	s_nop 0
	v_addc_co_u32_e32 v11, vcc, 0, v1, vcc
	v_add_co_u32_e32 v12, vcc, s0, v0
	s_mov_b32 s0, 0xb214000
	s_nop 0
	v_addc_co_u32_e32 v13, vcc, 0, v1, vcc
	v_add_co_u32_e32 v14, vcc, s0, v0
	s_mov_b32 s0, 0xb215000
	s_nop 0
	v_addc_co_u32_e32 v15, vcc, 0, v1, vcc
	v_add_co_u32_e32 v16, vcc, s0, v0
	s_mov_b32 s0, 0xb216000
	s_nop 0
	v_addc_co_u32_e32 v17, vcc, 0, v1, vcc
	v_add_co_u32_e32 v18, vcc, s0, v0
	s_mov_b32 s0, 0xb218000
	s_nop 0
	v_addc_co_u32_e32 v19, vcc, 0, v1, vcc
	v_add_co_u32_e32 v20, vcc, s0, v0
	s_mov_b32 s0, 0xb219000
	s_nop 0
	v_addc_co_u32_e32 v21, vcc, 0, v1, vcc
	v_add_co_u32_e32 v22, vcc, s0, v0
	s_mov_b32 s0, 0xb21a000
	s_nop 0
	v_addc_co_u32_e32 v23, vcc, 0, v1, vcc
	v_add_co_u32_e32 v24, vcc, s0, v0
	s_mov_b64 s[0:1], 0x19300000
	v_lshl_add_u64 v[2:3], v[2:3], 0, s[0:1]
	v_addc_co_u32_e32 v25, vcc, 0, v1, vcc
	s_mov_b32 s0, 0xb21b000
	s_waitcnt vmcnt(0)
	v_lshl_or_b32 v6, v26, 16, v5
	v_lshl_or_b32 v7, v28, 16, v27
	v_lshl_or_b32 v8, v30, 16, v29
	v_lshl_or_b32 v9, v9, 16, v31
	global_store_dwordx4 v[2:3], v[6:9], off offset:16
	global_load_ushort v5, v[10:11], off offset:1792
	s_nop 0
	global_load_ushort v6, v[12:13], off offset:2304
	global_load_ushort v7, v[14:15], off offset:2816
	global_load_ushort v8, v[16:17], off offset:3328
	global_load_ushort v9, v[18:19], off offset:3840
	global_load_ushort v26, v[20:21], off offset:256
	global_load_ushort v27, v[22:23], off offset:768
	global_load_ushort v28, v[24:25], off offset:1280
	v_add_co_u32_e32 v10, vcc, s0, v0
	s_mov_b32 s0, 0xb21c000
	s_nop 0
	v_addc_co_u32_e32 v11, vcc, 0, v1, vcc
	v_add_co_u32_e32 v12, vcc, s0, v0
	s_mov_b32 s0, 0xb21d000
	s_nop 0
	v_addc_co_u32_e32 v13, vcc, 0, v1, vcc
	v_add_co_u32_e32 v14, vcc, s0, v0
	s_mov_b32 s0, 0xb21e000
	s_nop 0
	v_addc_co_u32_e32 v15, vcc, 0, v1, vcc
	v_add_co_u32_e32 v16, vcc, s0, v0
	s_mov_b32 s0, 0xb21f000
	s_nop 0
	v_addc_co_u32_e32 v17, vcc, 0, v1, vcc
	v_add_co_u32_e32 v18, vcc, s0, v0
	s_mov_b32 s0, 0xb221000
	s_nop 0
	v_addc_co_u32_e32 v19, vcc, 0, v1, vcc
	v_add_co_u32_e32 v20, vcc, s0, v0
	s_mov_b32 s0, 0xb222000
	s_nop 0
	v_addc_co_u32_e32 v21, vcc, 0, v1, vcc
	v_add_co_u32_e32 v22, vcc, s0, v0
	s_mov_b32 s0, 0xb223000
	s_nop 0
	v_addc_co_u32_e32 v23, vcc, 0, v1, vcc
	v_add_co_u32_e32 v24, vcc, s0, v0
	s_mov_b32 s0, 0xb224000
	s_nop 0
	v_addc_co_u32_e32 v25, vcc, 0, v1, vcc
	s_waitcnt vmcnt(0)
	v_lshl_or_b32 v6, v6, 16, v5
	v_lshl_or_b32 v7, v8, 16, v7
	v_lshl_or_b32 v8, v26, 16, v9
	v_lshl_or_b32 v9, v28, 16, v27
	global_store_dwordx4 v[2:3], v[6:9], off offset:32
	global_load_ushort v5, v[10:11], off offset:1792
	s_nop 0
	global_load_ushort v6, v[12:13], off offset:2304
	global_load_ushort v7, v[14:15], off offset:2816
	global_load_ushort v8, v[16:17], off offset:3328
	global_load_ushort v9, v[18:19], off offset:3840
	global_load_ushort v26, v[20:21], off offset:256
	global_load_ushort v27, v[22:23], off offset:768
	global_load_ushort v28, v[24:25], off offset:1280
	v_add_co_u32_e32 v10, vcc, s0, v0
	s_mov_b32 s0, 0xb225000
	s_nop 0
	v_addc_co_u32_e32 v11, vcc, 0, v1, vcc
	v_add_co_u32_e32 v12, vcc, s0, v0
	s_mov_b32 s0, 0xb226000
	s_nop 0
	v_addc_co_u32_e32 v13, vcc, 0, v1, vcc
	v_add_co_u32_e32 v14, vcc, s0, v0
	s_mov_b32 s0, 0xb227000
	s_nop 0
	v_addc_co_u32_e32 v15, vcc, 0, v1, vcc
	v_add_co_u32_e32 v16, vcc, s0, v0
	s_mov_b32 s0, 0xb228000
	s_nop 0
	v_addc_co_u32_e32 v17, vcc, 0, v1, vcc
	v_add_co_u32_e32 v18, vcc, s0, v0
	s_mov_b32 s0, 0xb22a000
	s_nop 0
	v_addc_co_u32_e32 v19, vcc, 0, v1, vcc
	v_add_co_u32_e32 v20, vcc, s0, v0
	s_mov_b32 s0, 0xb22b000
	s_nop 0
	v_addc_co_u32_e32 v21, vcc, 0, v1, vcc
	v_add_co_u32_e32 v22, vcc, s0, v0
	s_mov_b32 s0, 0xb22c000
	s_nop 0
	v_addc_co_u32_e32 v23, vcc, 0, v1, vcc
	v_add_co_u32_e32 v24, vcc, s0, v0
	s_mov_b32 s0, 0xb22d000
	s_nop 0
	v_addc_co_u32_e32 v25, vcc, 0, v1, vcc
	s_waitcnt vmcnt(0)
	v_lshl_or_b32 v6, v6, 16, v5
	v_lshl_or_b32 v7, v8, 16, v7
	v_lshl_or_b32 v8, v26, 16, v9
	v_lshl_or_b32 v9, v28, 16, v27
	global_store_dwordx4 v[2:3], v[6:9], off offset:48
	global_load_ushort v5, v[10:11], off offset:1792
	s_nop 0
	global_load_ushort v6, v[12:13], off offset:2304
	global_load_ushort v7, v[14:15], off offset:2816
	global_load_ushort v8, v[16:17], off offset:3328
	global_load_ushort v9, v[18:19], off offset:3840
	global_load_ushort v26, v[20:21], off offset:256
	global_load_ushort v27, v[22:23], off offset:768
	global_load_ushort v28, v[24:25], off offset:1280
	v_add_co_u32_e32 v10, vcc, s0, v0
	s_mov_b32 s0, 0xb22e000
	s_nop 0
	v_addc_co_u32_e32 v11, vcc, 0, v1, vcc
	v_add_co_u32_e32 v12, vcc, s0, v0
	s_mov_b32 s0, 0xb22f000
	s_nop 0
	v_addc_co_u32_e32 v13, vcc, 0, v1, vcc
	v_add_co_u32_e32 v14, vcc, s0, v0
	s_mov_b32 s0, 0xb230000
	s_nop 0
	v_addc_co_u32_e32 v15, vcc, 0, v1, vcc
	v_add_co_u32_e32 v16, vcc, s0, v0
	s_mov_b32 s0, 0xb231000
	s_nop 0
	v_addc_co_u32_e32 v17, vcc, 0, v1, vcc
	v_add_co_u32_e32 v18, vcc, s0, v0
	s_mov_b32 s0, 0xb233000
	s_nop 0
	v_addc_co_u32_e32 v19, vcc, 0, v1, vcc
	v_add_co_u32_e32 v20, vcc, s0, v0
	s_mov_b32 s0, 0xb234000
	s_nop 0
	v_addc_co_u32_e32 v21, vcc, 0, v1, vcc
	v_add_co_u32_e32 v22, vcc, s0, v0
	s_mov_b32 s0, 0xb235000
	s_nop 0
	v_addc_co_u32_e32 v23, vcc, 0, v1, vcc
	v_add_co_u32_e32 v24, vcc, s0, v0
	s_mov_b32 s0, 0xb236000
	s_nop 0
	v_addc_co_u32_e32 v25, vcc, 0, v1, vcc
	s_waitcnt vmcnt(0)
	v_lshl_or_b32 v6, v6, 16, v5
	v_lshl_or_b32 v7, v8, 16, v7
	v_lshl_or_b32 v8, v26, 16, v9
	v_lshl_or_b32 v9, v28, 16, v27
	global_store_dwordx4 v[2:3], v[6:9], off offset:64
	global_load_ushort v5, v[10:11], off offset:1792
	s_nop 0
	global_load_ushort v6, v[12:13], off offset:2304
	global_load_ushort v7, v[14:15], off offset:2816
	global_load_ushort v8, v[16:17], off offset:3328
	global_load_ushort v9, v[18:19], off offset:3840
	global_load_ushort v26, v[20:21], off offset:256
	global_load_ushort v27, v[22:23], off offset:768
	global_load_ushort v28, v[24:25], off offset:1280
	v_add_co_u32_e32 v10, vcc, s0, v0
	s_mov_b32 s0, 0xb237000
	s_nop 0
	v_addc_co_u32_e32 v11, vcc, 0, v1, vcc
	v_add_co_u32_e32 v12, vcc, s0, v0
	s_mov_b32 s0, 0xb238000
	s_nop 0
	v_addc_co_u32_e32 v13, vcc, 0, v1, vcc
	v_add_co_u32_e32 v14, vcc, s0, v0
	s_mov_b32 s0, 0xb239000
	s_nop 0
	v_addc_co_u32_e32 v15, vcc, 0, v1, vcc
	v_add_co_u32_e32 v16, vcc, s0, v0
	s_mov_b32 s0, 0xb23a000
	s_nop 0
	v_addc_co_u32_e32 v17, vcc, 0, v1, vcc
	v_add_co_u32_e32 v18, vcc, s0, v0
	s_mov_b32 s0, 0xb23c000
	s_nop 0
	v_addc_co_u32_e32 v19, vcc, 0, v1, vcc
	v_add_co_u32_e32 v20, vcc, s0, v0
	s_mov_b32 s0, 0xb23d000
	s_nop 0
	v_addc_co_u32_e32 v21, vcc, 0, v1, vcc
	v_add_co_u32_e32 v22, vcc, s0, v0
	s_mov_b32 s0, 0xb23e000
	s_nop 0
	v_addc_co_u32_e32 v23, vcc, 0, v1, vcc
	v_add_co_u32_e32 v24, vcc, s0, v0
	s_mov_b32 s0, 0xb23f000
	s_nop 0
	v_addc_co_u32_e32 v25, vcc, 0, v1, vcc
	s_waitcnt vmcnt(0)
	v_lshl_or_b32 v6, v6, 16, v5
	v_lshl_or_b32 v7, v8, 16, v7
	v_lshl_or_b32 v8, v26, 16, v9
	v_lshl_or_b32 v9, v28, 16, v27
	global_store_dwordx4 v[2:3], v[6:9], off offset:80
	global_load_ushort v5, v[10:11], off offset:1792
	s_nop 0
	global_load_ushort v6, v[12:13], off offset:2304
	global_load_ushort v7, v[14:15], off offset:2816
	global_load_ushort v8, v[16:17], off offset:3328
	global_load_ushort v9, v[18:19], off offset:3840
	global_load_ushort v26, v[20:21], off offset:256
	global_load_ushort v27, v[22:23], off offset:768
	s_nop 0
	global_load_ushort v24, v[24:25], off offset:1280
	v_add_co_u32_e32 v10, vcc, s0, v0
	s_mov_b32 s0, 0xb240000
	s_nop 0
	v_addc_co_u32_e32 v11, vcc, 0, v1, vcc
	v_add_co_u32_e32 v12, vcc, s0, v0
	s_mov_b32 s0, 0xb241000
	s_nop 0
	v_addc_co_u32_e32 v13, vcc, 0, v1, vcc
	v_add_co_u32_e32 v14, vcc, s0, v0
	s_mov_b32 s0, 0xb242000
	s_nop 0
	v_addc_co_u32_e32 v15, vcc, 0, v1, vcc
	v_add_co_u32_e32 v16, vcc, s0, v0
	s_mov_b32 s0, 0xb243000
	s_nop 0
	v_addc_co_u32_e32 v17, vcc, 0, v1, vcc
	v_add_co_u32_e32 v18, vcc, s0, v0
	s_mov_b32 s0, 0xb245000
	s_nop 0
	v_addc_co_u32_e32 v19, vcc, 0, v1, vcc
	v_add_co_u32_e32 v20, vcc, s0, v0
	s_mov_b32 s0, 0xb246000
	s_nop 0
	v_addc_co_u32_e32 v21, vcc, 0, v1, vcc
	v_add_co_u32_e32 v22, vcc, s0, v0
	s_mov_b32 s0, 0xb247000
	s_nop 0
	v_addc_co_u32_e32 v23, vcc, 0, v1, vcc
	v_add_co_u32_e32 v0, vcc, s0, v0
	v_readlane_b32 s0, v255, 7
	s_nop 0
	v_addc_co_u32_e32 v1, vcc, 0, v1, vcc
	v_readlane_b32 s1, v255, 8
	s_lshl_b64 s[0:1], s[0:1], 2
	s_add_u32 s0, s8, s0
	s_addc_u32 s1, s9, s1
	s_waitcnt vmcnt(0)
	v_lshl_or_b32 v6, v6, 16, v5
	v_lshl_or_b32 v7, v8, 16, v7
	v_lshl_or_b32 v8, v26, 16, v9
	v_lshl_or_b32 v9, v24, 16, v27
	global_store_dwordx4 v[2:3], v[6:9], off offset:96
	global_load_ushort v5, v[10:11], off offset:1792
	s_nop 0
	global_load_ushort v6, v[12:13], off offset:2304
	global_load_ushort v7, v[14:15], off offset:2816
	global_load_ushort v10, v[16:17], off offset:3328
	global_load_ushort v11, v[18:19], off offset:3840
	s_nop 0
	global_load_ushort v12, v[20:21], off offset:256
	global_load_ushort v13, v[22:23], off offset:768
	global_load_ushort v14, v[0:1], off offset:1280
	v_mov_b32_e32 v0, 0x200
	v_lshl_add_u32 v54, v4, 3, v0
	v_mov_b32_e32 v15, v236
	v_mov_b64_e32 v[0:1], s[10:11]
	v_mad_u64_u32 v[8:9], s[4:5], v54, s6, v[0:1]
	s_waitcnt vmcnt(0)
	v_lshl_or_b32 v4, v6, 16, v5
	v_lshl_or_b32 v5, v10, 16, v7
	v_lshl_or_b32 v6, v12, 16, v11
	v_lshl_or_b32 v7, v14, 16, v13
	global_store_dwordx4 v[2:3], v[4:7], off offset:112
	s_nop 0
	v_and_b32_e32 v14, 15, v15
	v_bfe_u32 v17, v15, 4, 2
	v_lshlrev_b32_e32 v19, 2, v14
	v_lshlrev_b32_e32 v2, 6, v17
	v_or_b32_e32 v21, 8, v17
	v_lshlrev_b32_e32 v160, 4, v14
	v_or_b32_e32 v23, 0x100, v19
	v_min_u32_e32 v3, 9, v21
	v_or_b32_e32 v20, v2, v19
	v_lshl_add_u64 v[0:1], s[0:1], 0, v[160:161]
	v_or_b32_e32 v16, v2, v23
	v_lshlrev_b32_e32 v24, 6, v3
	s_mov_b64 s[0:1], 0x2000
	v_lshlrev_b32_e32 v160, 1, v20
	v_lshl_add_u64 v[4:5], v[0:1], 0, s[0:1]
	v_add_co_u32_e32 v0, vcc, s20, v0
	v_lshl_add_u64 v[10:11], v[8:9], 0, v[160:161]
	v_lshlrev_b32_e32 v160, 1, v16
	v_or_b32_e32 v22, v24, v19
	v_addc_co_u32_e32 v1, vcc, 0, v1, vcc
	v_lshl_add_u64 v[12:13], v[8:9], 0, v[160:161]
	v_lshlrev_b32_e32 v160, 1, v22
	global_load_dwordx4 v[0:3], v[0:1], off
	s_nop 0
	global_load_dwordx4 v[4:7], v[4:5], off offset:1024
	v_lshl_add_u64 v[8:9], v[8:9], 0, v[160:161]
	global_load_dwordx2 v[42:43], v[10:11], off offset:512
	global_load_dwordx2 v[40:41], v[12:13], off offset:512
	global_load_dwordx2 v[34:35], v[8:9], off offset:512
	v_and_b32_e32 v8, 63, v15
	v_and_b32_e32 v9, 4, v15
	v_lshlrev_b32_e32 v160, 3, v8
	v_cmp_eq_u32_e64 s[36:37], 0, v9
	v_cmp_gt_u32_e64 s[38:39], 8, v14
	v_and_b32_e32 v14, 12, v19
	v_lshl_add_u64 v[8:9], s[8:9], 0, v[160:161]
	s_mov_b64 s[0:1], 0x16f00000
	v_lshl_add_u64 v[12:13], v[8:9], 0, s[0:1]
	v_cvt_f32_ubyte0_e32 v8, v14
	v_mul_f32_e32 v8, 0xbf549a78, v8
	v_exp_f32_e32 v56, v8
	v_or_b32_e32 v8, 1, v14
	v_cvt_f32_ubyte0_e32 v8, v8
	v_mul_f32_e32 v8, 0xbf549a78, v8
	v_exp_f32_e32 v57, v8
	v_or_b32_e32 v8, 2, v14
	v_cvt_f32_ubyte0_e32 v8, v8
	v_mul_f32_e32 v8, 0xbf549a78, v8
	v_exp_f32_e32 v58, v8
	v_or_b32_e32 v8, 3, v14
	v_cvt_f32_ubyte0_e32 v8, v8
	v_mul_f32_e32 v8, 0xbf549a78, v8
	v_exp_f32_e32 v59, v8
	v_mad_i64_i32 v[8:9], s[0:1], v54, s6, 0
	v_add_u32_e32 v18, 0x100, v16
	v_or_b32_e32 v24, v24, v23
	v_or_b32_e32 v8, v8, v160
	v_cmp_gt_u32_e32 vcc, 10, v21
	v_lshlrev_b32_e64 v55, v17, 1
	v_lshl_add_u64 v[10:11], s[10:11], 0, v[160:161]
	v_lshl_add_u64 v[14:15], s[10:11], 0, v[8:9]
	v_lshlrev_b32_e32 v8, 1, v16
	v_lshlrev_b32_e32 v16, 1, v18
	v_lshlrev_b32_e32 v18, 1, v24
	v_lshlrev_b32_e32 v20, 1, v20
	v_lshlrev_b32_e32 v22, 1, v22
	v_mov_b32_e32 v21, 0
	s_branch .LBB0_508

.LBB0_531:
	s_andn2_saveexec_b64 s[2:3], s[42:43]
	s_cbranch_execz .LBB0_556
	v_readlane_b32 s0, v255, 7
	v_mov_b32_e32 v9, v236
	v_readlane_b32 s1, v255, 8
	s_lshl_b64 s[0:1], s[0:1], 2
	v_bfe_u32 v19, v9, 4, 2
	v_readlane_b32 s4, v254, 28
	v_and_b32_e32 v17, 15, v9
	v_or_b32_e32 v23, 8, v19
	v_readlane_b32 s5, v254, 29
	s_add_u32 s0, s4, s0
	v_min_u32_e32 v0, 9, v23
	s_addc_u32 s1, s5, s1
	v_lshlrev_b32_e32 v160, 4, v17
	v_readlane_b32 s6, v255, 11
	v_lshlrev_b32_e32 v21, 2, v17
	v_lshlrev_b32_e32 v12, 6, v19
	v_lshlrev_b32_e32 v24, 6, v0
	v_lshl_add_u64 v[0:1], s[0:1], 0, v[160:161]
	s_mov_b64 s[0:1], 0x2000
	v_readlane_b32 s7, v255, 12
	v_lshlrev_b32_e32 v56, 1, v81
	v_or_b32_e32 v18, 0x100, v21
	v_lshl_add_u64 v[4:5], v[0:1], 0, s[0:1]
	v_mov_b64_e32 v[10:11], s[6:7]
	s_movk_i32 s0, 0x1200
	v_or_b32_e32 v20, v12, v21
	v_or_b32_e32 v8, v12, v18
	v_mad_i64_i32 v[10:11], s[0:1], v56, s0, v[10:11]
	v_lshlrev_b32_e32 v160, 1, v20
	v_add_co_u32_e32 v0, vcc, s20, v0
	v_lshl_add_u64 v[12:13], v[10:11], 0, v[160:161]
	v_lshlrev_b32_e32 v160, 1, v8
	v_or_b32_e32 v22, v24, v21
	v_addc_co_u32_e32 v1, vcc, 0, v1, vcc
	v_lshl_add_u64 v[14:15], v[10:11], 0, v[160:161]
	v_lshlrev_b32_e32 v160, 1, v22
	global_load_dwordx4 v[0:3], v[0:1], off
	s_nop 0
	global_load_dwordx4 v[4:7], v[4:5], off offset:1024
	v_lshl_add_u64 v[10:11], v[10:11], 0, v[160:161]
	global_load_dwordx2 v[44:45], v[12:13], off offset:512
	global_load_dwordx2 v[42:43], v[14:15], off offset:512
	global_load_dwordx2 v[36:37], v[10:11], off offset:512
	v_and_b32_e32 v10, 63, v9
	v_and_b32_e32 v9, 4, v9
	v_cmp_eq_u32_e64 s[36:37], 0, v9
	v_and_b32_e32 v9, 12, v21
	v_cmp_gt_u32_e64 s[38:39], 8, v17
	v_cvt_f32_ubyte0_e32 v17, v9
	v_mul_f32_e32 v17, 0xbf549a78, v17
	v_exp_f32_e32 v58, v17
	v_or_b32_e32 v17, 1, v9
	v_cvt_f32_ubyte0_e32 v17, v17
	v_mul_f32_e32 v17, 0xbf549a78, v17
	v_exp_f32_e32 v59, v17
	v_or_b32_e32 v17, 2, v9
	v_or_b32_e32 v9, 3, v9
	v_cvt_f32_ubyte0_e32 v17, v17
	v_cvt_f32_ubyte0_e32 v9, v9
	v_mul_f32_e32 v17, 0xbf549a78, v17
	v_mul_f32_e32 v9, 0xbf549a78, v9
	v_exp_f32_e32 v60, v17
	v_exp_f32_e32 v61, v9
	v_lshlrev_b32_e32 v160, 3, v10
	v_add_u32_e32 v16, 0x100, v8
	v_or_b32_e32 v18, v24, v18
	v_mov_b32_e32 v63, 0
	v_lshl_add_u64 v[12:13], s[4:5], 0, v[160:161]
	s_mov_b64 s[0:1], 0x16f00000
	v_cmp_gt_u32_e32 vcc, 10, v23
	v_lshlrev_b32_e64 v57, v19, 1
	v_lshl_add_u64 v[10:11], s[6:7], 0, v[160:161]
	v_lshl_add_u64 v[14:15], v[12:13], 0, s[0:1]
	s_mov_b32 s14, 0
	v_lshlrev_b32_e32 v8, 1, v8
	v_lshlrev_b32_e32 v16, 1, v16
	v_lshlrev_b32_e32 v18, 1, v18
	v_lshlrev_b32_e32 v20, 1, v20
	v_lshlrev_b32_e32 v22, 1, v22
	v_mov_b32_e32 v62, v56
	v_mov_b32_e32 v21, 0
	v_mov_b32_e32 v38, 0
	v_mov_b32_e32 v39, v63
	v_mov_b32_e32 v40, 0
	v_mov_b32_e32 v41, v63
	s_branch .LBB0_534
.LBB0_533:
	s_or_b64 exec, exec, s[0:1]
	v_sub_u32_e32 v9, v17, v63
	v_cvt_f32_i32_e32 v9, v9
	s_waitcnt vmcnt(2)
	v_lshlrev_b32_e32 v200, 16, v196
	v_and_b32_e32 v201, 0xffff0000, v196
	v_lshlrev_b32_e32 v202, 16, v198
	v_and_b32_e32 v203, 0xffff0000, v198
	v_pk_add_f32 v[200:201], v[200:201], v[202:203] neg_lo:[0,1] neg_hi:[0,1]
	v_lshlrev_b32_e32 v198, 16, v199
	v_pk_add_f32 v[40:41], v[40:41], v[200:201]
	v_lshlrev_b32_e32 v200, 16, v197
	v_and_b32_e32 v201, 0xffff0000, v197
	v_and_b32_e32 v199, 0xffff0000, v199
	v_pk_add_f32 v[200:201], v[200:201], v[198:199] neg_lo:[0,1] neg_hi:[0,1]
	s_nop 0
	v_pk_add_f32 v[38:39], v[38:39], v[200:201]
	v_lshlrev_b32_e32 v36, 16, v34
	v_and_b32_e32 v37, 0xffff0000, v34
	s_add_i32 s14, s14, 1
	v_rcp_iflag_f32_e32 v32, v9
	v_lshlrev_b64 v[24:25], 11, v[24:25]
	v_lshl_add_u64 v[24:25], v[14:15], 0, v[24:25]
	v_add_u32_e32 v62, 1, v62
	v_pk_fma_f32 v[36:37], v[32:33], v[40:41], v[36:37] op_sel_hi:[0,1,1] neg_lo:[0,0,1] neg_hi:[0,0,1]
	v_cvt_pk_bf16_f32 v34, v36, v37
	v_lshlrev_b32_e32 v36, 16, v35
	v_and_b32_e32 v37, 0xffff0000, v35
	v_pk_fma_f32 v[32:33], v[32:33], v[38:39], v[36:37] op_sel_hi:[0,1,1] neg_lo:[0,0,1] neg_hi:[0,0,1]
	v_cvt_pk_bf16_f32 v35, v32, v33
	s_cmp_eq_u32 s14, 2
	v_mov_b32_e32 v21, v17
	v_mov_b32_e32 v44, v26
	v_mov_b32_e32 v45, v27
	v_mov_b32_e32 v42, v28
	v_mov_b32_e32 v43, v29
	v_mov_b32_e32 v36, v30
	v_mov_b32_e32 v37, v31
	global_store_dwordx2 v[24:25], v[34:35], off
	s_cbranch_scc1 .LBB0_556
.LBB0_534:
	v_readlane_b32 s0, v255, 11
	v_readlane_b32 s1, v255, 12
	v_add_u32_e32 v24, s14, v56
	s_cmp_gt_u32 s14, 0
	v_mov_b64_e32 v[26:27], s[0:1]
	s_movk_i32 s0, 0x1200
	v_mad_i64_i32 v[32:33], s[0:1], v24, s0, v[26:27]
	s_waitcnt vmcnt(0)
	v_mov_b32_e32 v26, v44
	v_mov_b32_e32 v27, v45
	v_mov_b32_e32 v28, v42
	v_mov_b32_e32 v29, v43
	v_mov_b32_e32 v30, v36
	v_mov_b32_e32 v31, v37
	s_cbranch_scc1 .LBB0_536
	v_lshl_add_u64 v[26:27], v[32:33], 0, s[34:35]
	v_mov_b32_e32 v9, v161
	v_mov_b32_e32 v17, v161
	v_lshl_add_u64 v[28:29], v[26:27], 0, v[8:9]
	v_lshl_add_u64 v[30:31], v[26:27], 0, v[16:17]
	v_mov_b32_e32 v19, v161
	v_lshl_add_u64 v[34:35], v[26:27], 0, v[18:19]
	global_load_dwordx2 v[26:27], v[28:29], off
	s_nop 0
	global_load_dwordx2 v[28:29], v[30:31], off
	s_nop 0
	global_load_dwordx2 v[30:31], v[34:35], off
